# half of the workgroups (by (bx>>3)&1) run the SWA-sample units before the HBM-bound GLA-sample units
# speedup vs baseline: 1.0249x; 1.0148x over previous
; __device__ __forceinline__ void swa_prompt_unit(const Args& a, unsigned char* lds, int unit, int tid) {
;     ...
;     for (int it = 0; it < 4; ++it) { const int e = tid + it * 512, j = e >> 3, c = e & 7; const int kpos = (blk - 1) * 128 + j; const bool valid = kpos >= 0;
;         const size_t row = (size_t)b * 2048 + (valid ? kpos : 0);
;         u32x4 raw = (u32x4){0u, 0u, 0u, 0u}, rawv = (u32x4){0u, 0u, 0u, 0u}; float kf[8];
;         if (valid) { raw = *(const u32x4*)(Z + row * DINP + ZKS + kvh * 64 + c * 8); rawv = *(const u32x4*)(Z + row * DINP + ZVS + kvh * 64 + c * 8); }
;         kf[0] = bflo(raw.x); kf[1] = bfhi(raw.x); kf[2] = bflo(raw.y); kf[3] = bfhi(raw.y); kf[4] = bflo(raw.z); kf[5] = bfhi(raw.z); kf[6] = bflo(raw.w); kf[7] = bfhi(raw.w);
;         if (c < 2 && valid) { const u32x4 pr = *(const u32x4*)(Z + row * DINP + ZKS + kvh * 64 + (c ^ 1) * 8);
;             float pf[8]; pf[0] = bflo(pr.x); pf[1] = bfhi(pr.x); pf[2] = bflo(pr.y); pf[3] = bfhi(pr.y); pf[4] = bflo(pr.z); pf[5] = bfhi(pr.z); pf[6] = bflo(pr.w); pf[7] = bfhi(pr.w);
;             const f32x2* rp = ROPE + kpos * 8; const float sg = c == 0 ? -1.f : 1.f;
; #pragma unroll
;             for (int d = 0; d < 8; ++d) { const f32x2 cs = rp[d]; kf[d] = kf[d] * cs.x + sg * pf[d] * cs.y; }
;             raw.x = cvt_pk_bf16(kf[0], kf[1]); raw.y = cvt_pk_bf16(kf[2], kf[3]); raw.z = cvt_pk_bf16(kf[4], kf[5]); raw.w = cvt_pk_bf16(kf[6], kf[7]);
;             kf[0] = bflo(raw.x); kf[1] = bfhi(raw.x); kf[2] = bflo(raw.y); kf[3] = bfhi(raw.y); kf[4] = bflo(raw.z); kf[5] = bfhi(raw.z); kf[6] = bflo(raw.w); kf[7] = bfhi(raw.w); }
;         *(u32x4*)(KL + j * 144 + c * 16) = raw;
;         bf16_t* vt = (bf16_t*)VTL + (c * 8) * 264 + j;
;         vt[0 * 264] = (bf16_t)(rawv.x & 0xffffu); vt[1 * 264] = (bf16_t)(rawv.x >> 16); vt[2 * 264] = (bf16_t)(rawv.y & 0xffffu); vt[3 * 264] = (bf16_t)(rawv.y >> 16);
;         vt[4 * 264] = (bf16_t)(rawv.z & 0xffffu); vt[5 * 264] = (bf16_t)(rawv.z >> 16); vt[6 * 264] = (bf16_t)(rawv.w & 0xffffu); vt[7 * 264] = (bf16_t)(rawv.w >> 16);
;         if (blk == 15 && j >= 128) { const size_t o = ((size_t)(b * 128 + (j - 128)) * 4 + kvh) * 64 + c * 8;
;             *(f32x4*)(a.out + OUT_KP + o) = (f32x4){kf[0], kf[1], kf[2], kf[3]}; *(f32x4*)(a.out + OUT_KP + o + 4) = (f32x4){kf[4], kf[5], kf[6], kf[7]};
.LBB0_255:
	s_bfe_u32 s98, s2, 0x10003
	s_cmpk_gt_i32 s2, 0x1ff
	s_movk_i32 s0, 0x1ff
	s_waitcnt vmcnt(0)
	s_barrier
	s_cbranch_scc1 .LBB0_432
	v_writelane_b32 v249, s90, 37
	s_add_u32 s4, s86, 0xa0000
	s_addc_u32 s5, s87, 0
	v_writelane_b32 v249, s91, 38
	v_writelane_b32 v249, s88, 39
	v_and_b32_e32 v1, 7, v188
	v_lshl_add_u32 v2, v1, 4, 0
	v_writelane_b32 v249, s89, 40
	v_writelane_b32 v249, s4, 41
	s_movk_i32 s1, 0x1070
	v_add_u32_e32 v5, 0x600, v188
	v_writelane_b32 v249, s5, 42
	v_cmp_gt_u32_e64 s[4:5], 2, v1
	v_cmp_lt_u32_e64 s[6:7], 1, v1
	v_lshlrev_b32_e32 v74, 3, v1
	v_cmp_eq_u32_e64 s[8:9], 0, v1
	v_mad_u32_u24 v1, v1, s1, v2
	v_lshrrev_b32_e32 v75, 3, v188
	v_lshrrev_b32_e32 v83, 3, v89
	s_add_u32 s92, s84, 0x8400000
	v_lshrrev_b32_e32 v105, 3, v5
	v_lshl_add_u32 v77, v75, 1, v1
	v_lshl_add_u32 v93, v83, 1, v1
	s_addc_u32 s93, s85, 0
	v_lshl_add_u32 v106, v105, 1, v1
	v_bfe_u32 v1, v188, 6, 1
	v_lshlrev_b32_e32 v90, 3, v86
	v_add_u32_e32 v6, 0, v31
	v_mov_b32_e32 v0, 0
	v_mul_u32_u24_e32 v3, 0x90, v75
	v_mul_u32_u24_e32 v4, 0x90, v83
	v_cmp_lt_u32_e64 s[10:11], s0, v188
	s_add_u32 s90, s84, 0x8500000
	v_mul_u32_u24_e32 v5, 0x90, v105
	v_lshrrev_b32_e32 v92, 7, v188
	v_lshlrev_b32_e32 v107, 2, v1
	v_lshlrev_b32_e32 v108, 2, v86
	v_sub_u32_e32 v7, v6, v90
	v_mul_u32_u24_e32 v8, 0x90, v124
	s_movk_i32 s0, 0x210
	v_lshl_or_b32 v178, v1, 6, v124
	s_mov_b32 s3, 0xc600000
	v_mbcnt_lo_u32_b32 v1, -1, 0
	v_xor_b32_e32 v76, 8, v74
	s_mov_b32 s63, 0
	s_addc_u32 s91, s85, 0
	v_or_b32_e32 v104, 0x80, v75
	v_cmp_gt_u32_e64 s[12:13], 2, v86
	v_cmp_eq_u32_e64 s[14:15], 0, v86
	v_or_b32_e32 v109, 2, v108
	v_or_b32_e32 v110, 3, v108
	v_or_b32_e32 v111, 16, v108
	v_or_b32_e32 v112, 17, v108
	v_or_b32_e32 v113, 18, v108
	v_or_b32_e32 v114, 19, v108
	v_or_b32_e32 v115, 32, v108
	v_or_b32_e32 v116, 33, v108
	v_or_b32_e32 v117, 34, v108
	v_or_b32_e32 v118, 35, v108
	v_or_b32_e32 v119, 48, v108
	v_or_b32_e32 v120, 49, v108
	v_or_b32_e32 v121, 50, v108
	v_or_b32_e32 v122, 51, v108
	v_or_b32_e32 v123, 64, v108
	v_or_b32_e32 v129, 0x41, v108
	v_or_b32_e32 v130, 0x42, v108
	v_or_b32_e32 v131, 0x43, v108
	v_or_b32_e32 v132, 0x50, v108
	v_or_b32_e32 v133, 0x51, v108
	v_or_b32_e32 v134, 0x52, v108
	v_or_b32_e32 v135, 0x53, v108
	v_or_b32_e32 v136, 0x60, v108
	v_or_b32_e32 v137, 0x61, v108
	v_or_b32_e32 v138, 0x62, v108
	v_or_b32_e32 v139, 0x63, v108
	v_or_b32_e32 v140, 0x70, v108
	v_or_b32_e32 v141, 0x71, v108
	v_or_b32_e32 v142, 0x72, v108
	v_or_b32_e32 v143, 0x73, v108
	v_or_b32_e32 v144, 0x81, v108
	v_or_b32_e32 v145, 0x82, v108
	v_or_b32_e32 v146, 0x83, v108
	v_or_b32_e32 v147, 0x90, v108
	v_or_b32_e32 v149, 0x91, v108
	v_or_b32_e32 v150, 0x92, v108
	v_or_b32_e32 v152, 0x93, v108
	v_or_b32_e32 v153, 0xa0, v108
	v_or_b32_e32 v154, 0xa1, v108
	v_or_b32_e32 v155, 0xa2, v108
	v_or_b32_e32 v156, 0xa3, v108
	v_or_b32_e32 v157, 0xb0, v108
	v_or_b32_e32 v158, 0xb1, v108
	v_or_b32_e32 v159, 0xb2, v108
	v_or_b32_e32 v160, 0xb3, v108
	v_or_b32_e32 v161, 0xc0, v108
	v_or_b32_e32 v162, 0xc1, v108
	v_or_b32_e32 v163, 0xc2, v108
	v_or_b32_e32 v164, 0xc3, v108
	v_or_b32_e32 v165, 0xd0, v108
	v_or_b32_e32 v166, 0xd1, v108
	v_or_b32_e32 v167, 0xd2, v108
	v_or_b32_e32 v168, 0xd3, v108
	v_or_b32_e32 v169, 0xe0, v108
	v_or_b32_e32 v170, 0xe1, v108
	v_or_b32_e32 v171, 0xe2, v108
	v_or_b32_e32 v172, 0xe3, v108
	v_or_b32_e32 v173, 0xf0, v108
	v_or_b32_e32 v174, 0xf1, v108
	v_or_b32_e32 v175, 0xf2, v108
	v_or_b32_e32 v176, 0xf3, v108
	v_mad_u32_u24 v177, v124, s0, v7
	v_bitop3_b32 v78, v31, s3, 16 bitop3:0xde
	v_mov_b32_e32 v79, v0
	v_lshlrev_b32_e32 v179, 6, v92
	v_or_b32_e32 v80, 0x24a00040, v90
	v_mov_b32_e32 v81, v0
	v_and_b32_e32 v82, 48, v188
	s_movk_i32 s89, 0x5e00
	v_add_u32_e32 v180, v2, v4
	v_lshlrev_b32_e32 v94, 1, v74
	v_add_u32_e32 v181, v2, v5
	v_mbcnt_hi_u32_b32 v151, -1, v1
	s_mov_b64 s[80:81], 0x5e000
	v_add_u32_e32 v182, v2, v3
	v_mov_b32_e32 v183, 0x2f00000
	v_mov_b32_e32 v185, 0xc00000
	v_add_u32_e32 v187, v6, v8
	v_mov_b32_e32 v190, 0xff61b1e6
	s_mov_b32 s88, s2
	s_mov_b32 s94, s2
	s_branch .LBB0_258

; __device__ __forceinline__ void gla_sample_unit(const Args& a, unsigned char* lds, int unit, int tid) {
;     const int lane = tid & 63, wave = tid >> 6;
;     const int b = unit >> 2, h = unit & 3;
;     float* Q4 = (float*)lds;
;     float* KD4 = Q4 + 1024;
;     float* KI4 = KD4 + 1024;
;     float* DECS = KI4 + 1024;
;     float* AS = DECS + 256;
;     float* RED = AS + 16;
;     float* VS = RED + 16;
;     float* ORED = VS + 2048;
;     const bf16_t* Z = (const bf16_t*)(a.ws + WS_Z); bf16_t* OCAT = (bf16_t*)(a.ws + WS_OCAT);
;     const size_t row0 = (size_t)MP + b * 4;
;     if (tid < 256) { const int kcol = tid; float la[4];
; #pragma unroll
;         for (int t = 0; t < 4; ++t) la[t] = a.b_a[h * 256 + kcol];
; #pragma unroll
;         for (int r = 0; r < 16; ++r) { const float w = a.w_a2[r * 1024 + h * 256 + kcol];
; #pragma unroll
;             for (int t = 0; t < 4; ++t) la[t] += bf2f(Z[(row0 + t) * DINP + ZAG + r]) * w; }
;         float bb[4]; float c = 0.f;
; #pragma unroll
;         for (int t = 0; t < 4; ++t) { c += logsig16(la[t]); bb[t] = c; }
;         f32x4 qv, kd, ki;
; #pragma unroll
;         for (int t = 0; t < 4; ++t) { const float q = bf2f(Z[(row0 + t) * DINP + ZQG + h * 256 + kcol]), k = bf2f(Z[(row0 + t) * DINP + ZKG + h * 256 + kcol]);
;             qv[t] = q * __expf(bb[t]) * 0.0625f; ki[t] = k * __expf(-bb[t]); kd[t] = k * __expf(c - bb[t]); }
;         *(f32x4*)(Q4 + kcol * 4) = qv; *(f32x4*)(KD4 + kcol * 4) = kd; *(f32x4*)(KI4 + kcol * 4) = ki; DECS[kcol] = __expf(c);
;     } else { const int j = tid - 256, t = j >> 6, c = j & 63; const u32x4 raw = *(const u32x4*)(Z + (row0 + t) * DINP + ZVG + h * 512 + c * 8);
;         float* d = VS + t * 512 + c * 8; *(f32x4*)d = (f32x4){bflo(raw.x), bfhi(raw.x), bflo(raw.y), bfhi(raw.y)}; *(f32x4*)(d + 4) = (f32x4){bflo(raw.z), bfhi(raw.z), bflo(raw.w), bfhi(raw.w)}; }
;     __syncthreads();
;     { const int pair = tid >> 5, sub = tid & 31, t = pair >> 2, m = pair & 3; float s = 0.f;
; #pragma unroll
;       for (int i = 0; i < 8; ++i) { const int k = sub + 32 * i; s += Q4[k * 4 + t] * KI4[k * 4 + m]; }
; #pragma unroll
;       for (int o = 1; o < 32; o <<= 1) s += __shfl_xor(s, o);
;       if (sub == 0) AS[t * 4 + m] = (m <= t) ? s : 0.f; }
;     const int kq = tid >> 7, vc = (tid & 127) * 4;
;     f32x4 vr[4], o[4];
.LBB0_382:
	s_cmp_eq_u32 s98, 2
	s_cbranch_scc1 .Lswap_p2
	v_mov_b32_e32 v251, v151
	s_branch .Lswap_p
.Lswap_p2:
	v_mov_b32_e32 v151, v251
.Lswap_p:
	v_add_u32_e32 v0, 0xffffff00, v188
	v_lshrrev_b32_e32 v94, 6, v0
	v_and_b32_e32 v2, 0x1f8, v91
	v_lshlrev_b32_e32 v0, 11, v94
	v_lshlrev_b32_e32 v1, 2, v2
	v_add3_u32 v134, 0, v0, v1
	v_and_b32_e32 v0, 31, v188
	v_lshlrev_b32_e32 v4, 2, v92
	v_lshlrev_b32_e32 v6, 4, v0
	v_add3_u32 v136, 0, v4, v6
	v_xor_b32_e32 v4, 1, v151
	v_cmp_lt_i32_e32 vcc, v4, v66
	s_movk_i32 s0, 0x100
	v_cmp_gt_u32_e64 s[4:5], s0, v188
	v_cndmask_b32_e32 v4, v151, v4, vcc
	v_lshlrev_b32_e32 v129, 2, v4
	v_xor_b32_e32 v4, 2, v151
	v_cmp_lt_i32_e32 vcc, v4, v66
	s_movk_i32 s0, 0xff
	v_lshlrev_b32_e32 v133, 2, v188
	v_cndmask_b32_e32 v4, v151, v4, vcc
	v_lshlrev_b32_e32 v130, 2, v4
	v_xor_b32_e32 v4, 4, v151
	v_cmp_lt_i32_e32 vcc, v4, v66
	v_lshl_add_u32 v138, v92, 4, 0
	v_cmp_lt_u32_e64 s[6:7], s0, v188
	v_cndmask_b32_e32 v4, v151, v4, vcc
	v_lshlrev_b32_e32 v131, 2, v4
	v_xor_b32_e32 v4, 8, v151
	v_bfe_u32 v3, v188, 5, 2
	v_cmp_lt_i32_e32 vcc, v4, v66
	v_cmp_eq_u32_e64 s[8:9], 0, v0
	v_and_b32_e32 v0, 0x1fc, v133
	v_mad_i32_i24 v141, v92, -12, v138
	s_movk_i32 s0, 0x1ffc
	v_lshlrev_b32_e32 v5, 2, v3
	v_cndmask_b32_e32 v4, v151, v4, vcc
	v_cmp_gt_u32_e64 s[10:11], v3, v92
	v_lshlrev_b32_e32 v96, 2, v0
	v_mad_u32_u24 v3, v92, s0, v141
	s_movk_i32 s0, 0xe800
	s_ashr_i32 s3, s2, 31
	v_lshlrev_b32_e32 v132, 2, v4
	v_add_u32_e32 v210, v3, v96
	v_mad_i32_i24 v3, v92, s0, v3
	v_and_b32_e32 v4, 0x7f, v188
	s_lshl_b64 s[0:1], s[2:3], 19
	v_add3_u32 v137, 0, v5, v6
	v_add_u32_e32 v139, v138, v5
	v_lshlrev_b32_e32 v100, 4, v4
	v_lshl_or_b32 v4, v92, 11, s0
	v_mov_b32_e32 v5, s1
	v_readlane_b32 s0, v249, 21
	v_readlane_b32 s16, v249, 5
	v_readlane_b32 s1, v249, 22
	v_mov_b32_e32 v97, 0
	v_lshl_add_u32 v135, v188, 4, 0
	v_mul_i32_i24_e32 v1, -12, v188
	v_mul_i32_i24_e32 v6, 0xfffff808, v92
	v_readlane_b32 s17, v249, 6
	v_readlane_b32 s18, v249, 7
	v_readlane_b32 s19, v249, 8
	v_readlane_b32 s20, v249, 9
	v_readlane_b32 s21, v249, 10
	v_readlane_b32 s28, v249, 17
	v_readlane_b32 s29, v249, 18
	v_readlane_b32 s30, v249, 19
	v_readlane_b32 s31, v249, 20
	s_ashr_i32 s1, s0, 31
	v_readlane_b32 s90, v249, 37
	v_mov_b32_e32 v95, v97
	s_mov_b32 s15, 0
	v_add_u32_e32 v140, 0, v96
	v_add_u32_e32 v142, 64, v138
	v_add_u32_e32 v143, 0x80, v138
	v_add_u32_e32 v144, 0xc0, v138
	v_add_u32_e32 v145, 0x100, v138
	v_add_u32_e32 v146, 0x140, v138
	v_add_u32_e32 v147, 0x180, v138
	v_add_u32_e32 v149, 0x1c0, v138
	v_add_u32_e32 v150, 0x200, v138
	v_add_u32_e32 v151, 0x240, v138
	v_add_u32_e32 v152, 0x280, v138
	v_add_u32_e32 v153, 0x2c0, v138
	v_add_u32_e32 v154, 0x300, v138
	v_add_u32_e32 v155, 0x340, v138
	v_add_u32_e32 v156, 0x380, v138
	v_add_u32_e32 v157, 0x3c0, v138
	v_add_u32_e32 v158, 0x400, v138
	v_add_u32_e32 v159, 0x440, v138
	v_add_u32_e32 v160, 0x480, v138
	v_add_u32_e32 v161, 0x4c0, v138
	v_add_u32_e32 v162, 0x500, v138
	v_add_u32_e32 v163, 0x540, v138
	v_add_u32_e32 v164, 0x580, v138
	v_add_u32_e32 v165, 0x5c0, v138
	v_add_u32_e32 v166, 0x600, v138
	v_add_u32_e32 v167, 0x640, v138
	v_add_u32_e32 v168, 0x680, v138
	v_add_u32_e32 v169, 0x6c0, v138
	v_add_u32_e32 v170, 0x700, v138
	v_add_u32_e32 v171, 0x740, v138
	v_add_u32_e32 v172, 0x780, v138
	v_add_u32_e32 v173, 0x7c0, v138
	v_add_u32_e32 v174, 0x800, v138
	v_add_u32_e32 v175, 0x840, v138
	v_add_u32_e32 v176, 0x880, v138
	v_add_u32_e32 v177, 0x8c0, v138
	v_add_u32_e32 v178, 0x900, v138
	v_add_u32_e32 v179, 0x940, v138
	v_add_u32_e32 v180, 0x980, v138
	v_add_u32_e32 v181, 0x9c0, v138
	v_add_u32_e32 v182, 0xa00, v138
	v_add_u32_e32 v183, 0xa40, v138
	v_add_u32_e32 v185, 0xa80, v138
	v_add_u32_e32 v187, 0xac0, v138
	v_add_u32_e32 v190, 0xb00, v138
	v_add_u32_e32 v191, 0xb40, v138
	v_add_u32_e32 v192, 0xb80, v138
	v_add_u32_e32 v193, 0xbc0, v138
	v_add_u32_e32 v194, 0xc00, v138
	v_add_u32_e32 v195, 0xc40, v138
	v_add_u32_e32 v196, 0xc80, v138
	v_add_u32_e32 v197, 0xcc0, v138
	v_add_u32_e32 v198, 0xd00, v138
	v_add_u32_e32 v199, 0xd40, v138
	v_add_u32_e32 v200, 0xd80, v138
	v_add_u32_e32 v201, 0xdc0, v138
	v_add_u32_e32 v202, 0xe00, v138
	v_add_u32_e32 v203, 0xe40, v138
	v_add_u32_e32 v204, 0xe80, v138
	v_add_u32_e32 v205, 0xec0, v138
	v_add_u32_e32 v206, 0xf00, v138
	v_add_u32_e32 v207, 0xf40, v138
	v_add_u32_e32 v208, 0xf80, v138
	v_add_u32_e32 v209, 0xfc0, v138
	v_add_u32_e32 v211, v3, v96
	v_cmp_eq_u32_e64 s[12:13], 0, v186
	v_lshl_add_u32 v212, v148, 2, 0
	v_mov_b32_e32 v93, v97
	v_lshl_add_u64 v[98:99], s[20:21], 0, v[96:97]
	v_mov_b32_e32 v101, v97
	v_lshl_add_u64 v[102:103], s[72:73], 0, v[4:5]
	s_lshl_b64 s[16:17], s[0:1], 19
	v_lshl_add_u64 v[104:105], s[84:85], 0, v[4:5]
	s_movk_i32 s3, 0x5e00
	v_lshlrev_b32_e32 v106, 1, v2
	v_mov_b32_e32 v213, 0x5000
	v_mov_b32_e32 v214, 0x1780b000
	v_mov_b32_e32 v215, 0x17811000
	v_mov_b32_e32 v216, 0x17817000
	s_movk_i32 s19, 0x2000
	v_mov_b32_e32 v217, 0xffff
	s_mov_b32 s28, 0xbfb8aa3b
	s_mov_b32 s29, 0x800000
	s_mov_b32 s30, 0x3f317217
	s_mov_b32 s31, 0x7f800000
	s_mov_b32 s18, 0x3d800000
	v_add_u32_e32 v218, v135, v1
	s_mov_b32 s34, 0xb668000
	s_mov_b32 s35, 0xb66a000
	s_mov_b32 s36, 0xb66c000
	s_mov_b32 s37, 0xb66e000
	s_mov_b32 s38, 0xb670000
	s_mov_b32 s39, 0xb672000
	s_mov_b32 s40, 0xb674000
	s_mov_b32 s41, 0xb676000
	s_mov_b32 s42, 0xb678000
	s_mov_b32 s43, 0xb67a000
	s_mov_b32 s44, 0xb67c000
	s_mov_b32 s45, 0xb67e000
	v_add_u32_e32 v219, v3, v6
	v_mov_b32_e32 v220, 0x358637bd
	v_lshlrev_b32_e32 v96, 1, v0
	s_movk_i32 s46, 0x1800
	v_mov_b32_e32 v221, 0x41b17218
	s_mov_b32 s47, s2
	v_readlane_b32 s88, v249, 39
	v_readlane_b32 s91, v249, 38
	v_readlane_b32 s22, v249, 11
	v_readlane_b32 s23, v249, 12
	v_readlane_b32 s24, v249, 13
	v_readlane_b32 s25, v249, 14
	v_readlane_b32 s26, v249, 15
	v_readlane_b32 s27, v249, 16
	v_readlane_b32 s89, v249, 40
	s_cmp_lg_u32 s98, 1
	s_cbranch_scc1 .LBB0_384
	v_mov_b32_e32 v250, v66
	s_branch .LBB0_392
.Lswap_g_exit:
	s_cmp_eq_u32 s98, 2
	s_cbranch_scc1 .Lswap_cont
	s_branch .LBB0_392

; __global__ void __launch_bounds__(512, 2) hybrid_fwd(Args a) {
;     ...
;         for (int u = bx; u < 512; u += G) swa_prompt_unit(a, lds, u, tid);
;         for (int u = bx; u < 512; u += G) gla_sample_unit(a, lds, u, tid);
;         for (int u = bx; u < 512; u += G) swa_sample_unit(a, lds, u, tid);
;         xcd_barrier(xbar);
.LBB0_432:
	s_cmp_eq_u32 s98, 1
	s_cbranch_scc0 .Lswap_cont
	s_mov_b32 s98, 2
	v_mov_b32_e32 v66, v250
	s_branch .LBB0_382
